# grid-barrier poll interval s_sleep 32 -> 4
# speedup vs baseline: 1.1750x; 1.0122x over previous
.LBB0_100:
	s_sleep 4
	global_load_dword v16, v17, s[34:35] sc1
	s_waitcnt vmcnt(0)
	v_cmp_gt_u32_e32 vcc, s59, v16
	s_cbranch_vccnz .LBB0_100

.LBB0_1750:
	s_sleep 4
	global_load_dword v0, v17, s[6:7] sc1
	s_waitcnt vmcnt(0)
	v_cmp_gt_u32_e32 vcc, s36, v0
	s_cbranch_vccnz .LBB0_1750
	s_getpc_b64 s[98:99]
